# PH4 unit prologue: first mask-word load hoisted beside the K/V/Q prologue loads (global load), one exposed latency less per attention unit
# speedup vs baseline: 1.0045x; 1.0045x over previous
; template <bool MASK>
; DI void attn_unit(LAS unsigned char* lds, const bf16_t* qrow, const bf16_t* kbase, int kpitch, const bf16_t* vtbase, int vtpitch, int ntiles,
;                   const unsigned long long* maskp, bf16_t* orow, float c1, float c2) {
;     const int tid = fresh_tid(), lane = tid & 63, r = lane & 31, h = lane >> 5;
;     bf16x8 qf[8];
; #pragma unroll
;     for (int ks = 0; ks < 8; ++ks) qf[ks] = *(const bf16x8*)(qrow + 16 * ks + 8 * h);
;     f32x16 o[4];
; #pragma unroll
;     for (int d = 0; d < 4; ++d)
; #pragma unroll
;         for (int i = 0; i < 16; ++i) o[d][i] = 0.f;
;     float l = 0.f;
;     u32x4 pk[2], pv[2];
;     const int ke0 = tid, ke1 = tid + 512;
;     const bf16_t* kg0 = kbase + (size_t)(ke0 >> 4) * kpitch + (ke0 & 15) * 8; const bf16_t* kg1 = kbase + (size_t)(ke1 >> 4) * kpitch + (ke1 & 15) * 8;
;     const int kl0 = (ke0 >> 4) * AK_PITCH + (ke0 & 15) * 16, kl1 = (ke1 >> 4) * AK_PITCH + (ke1 & 15) * 16;
;     const bf16_t* vg0 = vtbase + (size_t)(ke0 >> 3) * vtpitch + (ke0 & 7) * 8; const bf16_t* vg1 = vtbase + (size_t)(ke1 >> 3) * vtpitch + (ke1 & 7) * 8;
;     const int vl0 = AK_BYTES + (ke0 >> 3) * AV_PITCH + (ke0 & 7) * 16, vl1 = AK_BYTES + (ke1 >> 3) * AV_PITCH + (ke1 & 7) * 16;
;     pk[0] = *(const u32x4*)kg0; pk[1] = *(const u32x4*)kg1; pv[0] = *(const u32x4*)vg0; pv[1] = *(const u32x4*)vg1;
;     {
;         LAS unsigned char* nb = lds;
;         *(LAS u32x4*)(nb + kl0) = pk[0]; *(LAS u32x4*)(nb + kl1) = pk[1];
; __global__ void __launch_bounds__(512, 2) fwd_megakernel(Args args) {
;     ...
;             for (int k = 0; k < (512 + G - 1) / G; ++k) {
;                 const int it = k * G + c;
;                 if (it < 512) {
;                     const int kk = it / 256, cc = it % 256;
;                     const int bk = cc & 7, j = cc >> 3, qb = kk ? (63 - j) : j, b = bk >> 1, kvh = bk & 1;
;                     const int gh = wave & 3, half = wave >> 2, hq = kvh * 4 + gh;
;                     const int tq = qb * 64 + half * 32 + (lane & 31);
;                     const size_t qr = (size_t)b * S_ + tq;
;     ...
;                     attn_unit<true>(lds, Q + qr * 1024 + hq * 128, Kb + (size_t)b * S_ * 256 + kvh * 128, 256, VT + (size_t)bk * 128 * S_, S_, qb + 1,
;                                     MASK + (size_t)b * 64 * S_ + tq, OA + qr * 1024 + hq * 128, 0.08838834764831845f * 1.4426950408889634f, c2a);
.LBB0_1240:
	s_mul_i32 s2, s15, s66
	s_add_i32 s2, s2, s86
	s_cmpk_gt_i32 s2, 0x1ff
	s_cbranch_scc1 .LBB0_1239
	s_ashr_i32 s3, s2, 31
	s_lshr_b32 s3, s3, 24
	s_add_i32 s3, s2, s3
	s_and_b32 s3, s3, 0xffffff00
	s_sub_i32 s3, s2, s3
	s_ashr_i32 s16, s3, 3
	s_and_b32 s17, s3, 7
	s_addk_i32 s2, 0xff
	s_sub_i32 s18, 63, s16
	s_cmpk_lt_u32 s2, 0x1ff
	s_cselect_b32 s16, s16, s18
	s_lshl_b32 s18, s16, 6
	s_bfe_u32 s2, s3, 0x20001
	s_and_b32 s3, s3, 1
	v_add_u32_e32 v66, s18, v179
	v_ashrrev_i32_e32 v67, 31, v66
	s_lshl_b32 s18, s3, 9
	s_lshl_b32 s70, s2, 22
	v_lshlrev_b64 v[0:1], 10, v[66:67]
	s_or_b32 s18, s18, s8
	v_lshl_add_u64 v[144:145], v[0:1], 0, s[70:71]
	s_lshl_b32 s70, s18, 1
	s_lshl_b32 s18, s2, 21
	s_add_u32 s2, s9, s18
	s_addc_u32 s19, s10, 0
	s_lshl_b32 s22, s3, 8
	v_mov_b32_e32 v65, v186
	s_add_u32 s2, s2, s22
	s_addc_u32 s3, s19, 0
	v_add_u32_e32 v16, 0x200, v65
	v_ashrrev_i32_e32 v0, 4, v65
	s_lshl_b32 s19, s17, 20
	v_ashrrev_i32_e32 v1, 31, v0
	v_ashrrev_i32_e32 v6, 4, v16
	v_ashrrev_i32_e32 v10, 3, v65
	v_ashrrev_i32_e32 v16, 3, v16
	s_add_u32 s30, s11, s19
	v_lshlrev_b64 v[68:69], 9, v[0:1]
	v_lshlrev_b32_e32 v1, 4, v65
	v_ashrrev_i32_e32 v7, 31, v6
	v_ashrrev_i32_e32 v11, 31, v10
	v_ashrrev_i32_e32 v17, 31, v16
	s_addc_u32 s31, s12, 0
	v_lshl_add_u64 v[2:3], s[2:3], 0, v[68:69]
	v_and_b32_e32 v4, 0xf0, v1
	v_mov_b32_e32 v5, v161
	v_lshlrev_b64 v[70:71], 9, v[6:7]
	v_lshlrev_b64 v[72:73], 13, v[10:11]
	v_lshlrev_b64 v[74:75], 13, v[16:17]
	v_lshl_add_u64 v[2:3], v[2:3], 0, v[4:5]
	v_lshl_add_u64 v[8:9], s[2:3], 0, v[70:71]
	v_lshl_add_u64 v[12:13], s[30:31], 0, v[72:73]
	v_and_b32_e32 v14, 0x70, v1
	v_mov_b32_e32 v15, v161
	v_lshl_add_u64 v[18:19], s[30:31], 0, v[74:75]
	v_lshl_add_u64 v[8:9], v[8:9], 0, v[4:5]
	v_lshl_add_u64 v[12:13], v[12:13], 0, v[14:15]
	v_lshl_add_u64 v[18:19], v[18:19], 0, v[14:15]
	flat_load_dwordx4 v[96:99], v[2:3]
	flat_load_dwordx4 v[100:103], v[8:9]
	flat_load_dwordx4 v[104:107], v[12:13]
	flat_load_dwordx4 v[108:111], v[18:19]
	s_movk_i32 s17, 0x110
	v_mad_u64_u32 v[146:147], s[2:3], v0, s17, v[4:5]
	v_mad_u64_u32 v[148:149], s[2:3], v6, s17, v[4:5]
	s_movk_i32 s17, 0x88
	v_mad_u64_u32 v[150:151], s[2:3], v10, s17, v[14:15]
	v_mad_u64_u32 v[152:153], s[2:3], v16, s17, v[14:15]
	v_add_u32_e32 v0, 0, v150
	v_add_u32_e32 v1, 0, v152
	v_bfe_u32 v76, v65, 5, 1
	v_add_u32_e32 v4, 0x4400, v0
	v_add_u32_e32 v5, 0x4400, v1
	v_lshl_add_u64 v[0:1], v[144:145], 1, s[4:5]
	v_lshlrev_b32_e32 v160, 4, v76
	v_lshl_add_u64 v[0:1], v[0:1], 0, s[70:71]
	v_lshl_add_u64 v[0:1], v[0:1], 0, v[160:161]
	flat_load_dwordx4 v[112:115], v[0:1]
	flat_load_dwordx4 v[116:119], v[0:1] offset:32
	flat_load_dwordx4 v[120:123], v[0:1] offset:64
	flat_load_dwordx4 v[124:127], v[0:1] offset:96
	flat_load_dwordx4 v[128:131], v[0:1] offset:128
	flat_load_dwordx4 v[132:135], v[0:1] offset:160
	flat_load_dwordx4 v[136:139], v[0:1] offset:192
	flat_load_dwordx4 v[140:143], v[0:1] offset:224
	s_add_u32 s2, s13, s18
	v_add_u32_e32 v2, 0, v146
	s_addc_u32 s3, s14, 0
	v_add_u32_e32 v3, 0, v148
	v_lshl_add_u64 v[0:1], v[66:67], 3, s[2:3]
	global_load_dwordx2 v[176:177], v[0:1], off
	s_mov_b64 s[2:3], -1
	s_cmp_gt_i32 s16, -1
	v_lshlrev_b32_e32 v147, 2, v76
	s_waitcnt vmcnt(0) lgkmcnt(0)
	ds_write_b128 v2, v[96:99]
	ds_write_b128 v3, v[100:103]
	ds_write2_b64 v4, v[104:105], v[106:107] offset1:1
	ds_write2_b64 v5, v[108:109], v[110:111] offset1:1
	s_waitcnt lgkmcnt(0)
	s_barrier
	s_cbranch_scc1 .LBB0_1243
	v_lshlrev_b32_e32 v64, 2, v76
	s_mov_b64 s[2:3], 0
